# P2 work queue: next index fetched (returning atomic) one key-tile before a FoX unit ends / at the start of a retention KV unit, instead of after the unit; fetch site only waits
# baseline (speedup 1.0000x reference)
.LBB0_439:
	s_cmp_lt_i32 s92, 3
	s_cselect_b64 s[0:1], -1, 0
	s_and_b64 s[4:5], s[0:1], s[4:5]
	v_bfe_u32 v133, v223, 5, 1
	s_andn2_b64 vcc, exec, s[4:5]
	v_and_b32_e32 v177, 16, v223
	v_and_b32_e32 v176, 31, v223
	v_lshlrev_b32_e32 v180, 4, v133
	v_lshlrev_b32_e32 v178, 2, v133
	s_cbranch_vccnz .LBB0_483
	v_readlane_b32 s4, v252, 8
	s_waitcnt vmcnt(0)
	v_lshlrev_b32_e32 v0, 2, v224
	v_readlane_b32 s16, v252, 20
	v_readlane_b32 s17, v252, 21
	v_readlane_b32 s18, v252, 22
	v_readlane_b32 s19, v252, 23
	s_nop 2
	global_load_dword v3, v0, s[16:17]
	s_nop 0
	global_load_dword v4, v0, s[18:19]
	v_mbcnt_lo_u32_b32 v2, -1, 0
	v_lshrrev_b32_e32 v135, 8, v223
	v_lshrrev_b32_e32 v5, 2, v223
	v_bfe_u32 v146, v223, 2, 6
	v_lshlrev_b32_e32 v6, 4, v223
	v_mul_u32_u24_e32 v10, 0x90, v176
	v_mbcnt_hi_u32_b32 v11, -1, v2
	v_and_b32_e32 v2, 48, v6
	v_bitop3_b32 v5, v5, 63, v5 bitop3:0xc
	v_mul_u32_u24_e32 v6, 0x4800, v135
	v_mul_u32_u24_e32 v12, 0x90, v146
	v_add3_u32 v152, 0, v180, v10
	v_and_b32_e32 v10, 64, v11
	v_xor_b32_e32 v15, 1, v11
	v_cvt_f32_ubyte0_e32 v153, v5
	v_add3_u32 v5, 0, v6, v12
	v_lshlrev_b32_e32 v6, 1, v2
	v_lshlrev_b32_e32 v136, 1, v2
	v_add_u32_e32 v2, 64, v10
	v_readlane_b32 s8, v252, 12
	v_bfe_u32 v7, v223, 2, 2
	v_cmp_lt_i32_e32 vcc, v15, v2
	v_readlane_b32 s6, v252, 10
	v_readlane_b32 s9, v252, 13
	s_add_u32 s8, s30, 0x3800
	v_lshl_or_b32 v13, v133, 3, v7
	v_or_b32_e32 v7, v178, v7
	v_add_u32_e32 v160, v5, v6
	v_cndmask_b32_e32 v5, v11, v15, vcc
	v_lshlrev_b32_e32 v8, 2, v223
	s_addc_u32 s9, s31, 0
	s_add_i32 s6, 0, 0x12000
	v_mul_u32_u24_e32 v159, 0x90, v7
	v_lshlrev_b32_e32 v5, 2, v5
	v_and_or_b32 v151, v8, 12, v177
	v_add_u32_e32 v156, s6, v8
	v_xor_b32_e32 v16, 2, v11
	v_cmp_lt_i32_e32 vcc, v16, v2
	v_xor_b32_e32 v17, 4, v11
	v_xor_b32_e32 v18, 8, v11
	v_cndmask_b32_e32 v6, v11, v16, vcc
	v_lshlrev_b32_e32 v6, 2, v6
	v_cmp_lt_i32_e32 vcc, v17, v2
	v_xor_b32_e32 v19, 16, v11
	v_xor_b32_e32 v20, 32, v11
	s_add_u32 s50, s30, 0xd000000
	v_lshrrev_b32_e32 v132, 3, v223
	v_and_b32_e32 v9, 7, v223
	s_addc_u32 s51, s31, 0
	v_readlane_b32 s5, v252, 9
	v_readlane_b32 s7, v252, 11
	v_readlane_b32 s10, v252, 14
	v_readlane_b32 s11, v252, 15
	v_readlane_b32 s12, v252, 16
	v_readlane_b32 s13, v252, 17
	v_lshlrev_b32_e32 v0, 3, v133
	v_mov_b32_e32 v147, 0x7f
	s_movk_i32 s4, 0x80
	v_lshlrev_b32_e32 v134, 3, v9
	v_mul_u32_u24_e32 v14, 0x90, v132
	v_lshlrev_b32_e32 v9, 4, v9
	s_add_u32 s52, s30, 0x2780000
	s_mov_b32 s7, 0
	v_mov_b32_e32 v1, 0
	v_lshl_or_b32 v148, v133, 8, v176
	v_add_u32_e32 v149, 0xf00, v223
	s_movk_i32 s3, 0x5ff
	s_mov_b32 s27, 0xc2fc0000
	s_mov_b32 s35, 0x800000
	s_movk_i32 s48, 0x1000
	s_movk_i32 s49, 0x1c00
	v_lshl_or_b32 v150, v224, 7, v147
	v_cmp_gt_u32_e64 s[4:5], s4, v223
	v_mul_u32_u24_e32 v154, 0x90, v13
	v_add3_u32 v155, 0, v14, v9
	v_add_u32_e32 v157, s6, v180
	v_lshlrev_b32_e32 v158, 1, v151
	s_addc_u32 s53, s31, 0
	s_waitcnt vmcnt(1)
	v_and_b32_e32 v7, 0x7fffffff, v3
	s_waitcnt vmcnt(0)
	v_and_b32_e32 v8, 0x7fffffff, v4
	ds_bpermute_b32 v7, v5, v7
	ds_bpermute_b32 v5, v5, v8
	v_max_f32_e64 v3, |v3|, |v3|
	v_max_f32_e64 v4, |v4|, |v4|
	s_add_i32 s54, 0, 0x23f80
	s_waitcnt lgkmcnt(1)
	v_max_f32_e32 v7, v7, v7
	s_waitcnt lgkmcnt(0)
	v_max_f32_e32 v5, v5, v5
	v_max_f32_e32 v3, v3, v7
	v_max_f32_e32 v4, v4, v5
	ds_bpermute_b32 v5, v6, v3
	ds_bpermute_b32 v6, v6, v4
	v_cndmask_b32_e32 v7, v11, v17, vcc
	v_lshlrev_b32_e32 v7, 2, v7
	v_cmp_lt_i32_e32 vcc, v18, v2
	s_waitcnt lgkmcnt(1)
	v_max_f32_e32 v5, v5, v5
	s_waitcnt lgkmcnt(0)
	v_max_f32_e32 v6, v6, v6
	v_max_f32_e32 v3, v3, v5
	v_max_f32_e32 v4, v4, v6
	ds_bpermute_b32 v5, v7, v3
	ds_bpermute_b32 v6, v7, v4
	v_cndmask_b32_e32 v7, v11, v18, vcc
	v_lshlrev_b32_e32 v7, 2, v7
	v_cmp_lt_i32_e32 vcc, v19, v2
	s_waitcnt lgkmcnt(1)
	v_max_f32_e32 v5, v5, v5
	s_waitcnt lgkmcnt(0)
	v_max_f32_e32 v6, v6, v6
	v_max_f32_e32 v3, v3, v5
	v_max_f32_e32 v4, v4, v6
	ds_bpermute_b32 v5, v7, v3
	ds_bpermute_b32 v6, v7, v4
	v_cndmask_b32_e32 v7, v11, v19, vcc
	v_lshlrev_b32_e32 v7, 2, v7
	v_cmp_lt_i32_e32 vcc, v20, v2
	s_waitcnt lgkmcnt(1)
	v_max_f32_e32 v5, v5, v5
	s_waitcnt lgkmcnt(0)
	v_max_f32_e32 v6, v6, v6
	v_max_f32_e32 v3, v3, v5
	v_max_f32_e32 v4, v4, v6
	ds_bpermute_b32 v5, v7, v3
	ds_bpermute_b32 v6, v7, v4
	v_cndmask_b32_e32 v2, v11, v20, vcc
	v_lshlrev_b32_e32 v161, 2, v2
	v_lshlrev_b32_e32 v138, 1, v0
	s_waitcnt lgkmcnt(1)
	v_max_f32_e32 v2, v5, v5
	s_waitcnt lgkmcnt(0)
	v_max_f32_e32 v5, v6, v6
	v_max_f32_e32 v2, v3, v2
	v_max_f32_e32 v3, v4, v5
	ds_bpermute_b32 v4, v161, v2
	ds_bpermute_b32 v5, v161, v3
	s_mov_b64 s[10:11], 0x1000
	s_mov_b32 s55, 0x70000
	s_mov_b64 s[12:13], 0x4000400
	s_waitcnt lgkmcnt(1)
	v_max_f32_e32 v4, v4, v4
	s_waitcnt lgkmcnt(0)
	v_max_f32_e32 v5, v5, v5
	v_max_f32_e32 v2, v2, v4
	v_max_f32_e32 v3, v3, v5
	v_mul_f32_e32 v2, 0x41000000, v2
	v_mul_f32_e32 v2, v3, v2
	v_mul_f32_e32 v2, 0x3fb8aa3b, v2
	v_fmaak_f32 v162, 2.0, v2, 0x42200000
	s_brev_b32 s56, 32
	v_mov_b32_e32 v163, 0x42800000
	v_mov_b32_e32 v164, 0x42000000
	v_not_b32_e32 v165, 63
	v_mov_b32_e32 v166, 0x1c00
	v_mov_b32_e32 v167, 0xff800000
	v_readlane_b32 s14, v252, 18
	v_readlane_b32 s15, v252, 19
	s_and_saveexec_b64 s[98:99], s[90:91]
	s_cbranch_execz .Lq_pre
	v_mov_b32_e32 v200, 1
	global_atomic_add v199, v1, v200, s[8:9] sc0
.Lq_pre:
	s_or_b64 exec, exec, s[98:99]
	s_branch .LBB0_445

.LBB0_445:
	s_and_saveexec_b64 s[14:15], s[90:91]
	s_cbranch_execz .LBB0_449
	s_mov_b64 s[18:19], exec
	v_mbcnt_lo_u32_b32 v0, s18, 0
	v_mbcnt_hi_u32_b32 v0, s19, v0
	v_cmp_eq_u32_e32 vcc, 0, v0
	s_and_saveexec_b64 s[16:17], vcc
	s_cbranch_execz .LBB0_448
	s_waitcnt vmcnt(0)
	v_mov_b32_e32 v2, v199
.LBB0_448:
	s_or_b64 exec, exec, s[16:17]
	s_nop 0
	v_readfirstlane_b32 s6, v2
	v_mov_b32_e32 v2, s54
	s_nop 0
	v_add_u32_e32 v0, s6, v0
	ds_write_b32 v2, v0
.LBB0_449:
	s_or_b64 exec, exec, s[14:15]
	v_mov_b32_e32 v0, s54
	s_waitcnt lgkmcnt(0)
	s_barrier
	ds_read_b32 v0, v0
	s_mov_b64 s[14:15], -1
	s_waitcnt lgkmcnt(0)
	s_barrier
	v_cmp_lt_i32_e32 vcc, s3, v0
	v_readfirstlane_b32 s16, v0
	s_cbranch_vccnz .LBB0_444
	s_cmpk_gt_i32 s16, 0x1ff
	s_cbranch_scc0 .LBB0_452
	s_and_saveexec_b64 s[98:99], s[90:91]
	s_cbranch_execz .Lq_kv
	v_mov_b32_e32 v200, 1
	global_atomic_add v199, v1, v200, s[8:9] sc0
.Lq_kv:
	s_or_b64 exec, exec, s[98:99]
	s_add_i32 s6, s16, 0xfffffe00
	s_bfe_u32 s17, s6, 0x30005
	v_cvt_f32_ubyte0_e32 v0, s17
	v_sub_f32_e32 v0, 0xc0a00000, v0
	v_cmp_gt_f32_e32 vcc, s27, v0
	s_lshr_b32 s18, s6, 5
	s_and_b64 s[14:15], vcc, exec
	v_cndmask_b32_e32 v2, 0, v163, vcc
	v_add_f32_e32 v0, v0, v2
	v_exp_f32_e32 v0, v0
	s_cselect_b32 s14, 0xffffffc0, 0
	v_mov_b32_e32 v137, v1
	v_ldexp_f32 v0, v0, s14
	v_sub_f32_e32 v18, 1.0, v0
	v_cmp_gt_f32_e32 vcc, s35, v18
	s_and_b64 s[14:15], vcc, exec
	s_cselect_b32 s15, 32, 0
	s_lshl_b32 s14, s6, 4
	s_lshl_b32 s6, s6, 1
	s_and_b32 s19, s14, 0x3000
	s_and_b32 s14, s6, 62
	v_add_u32_e32 v0, s14, v135
	v_lshl_add_u32 v0, v0, 6, s19
	v_or_b32_e32 v0, v0, v146
	v_mul_u32_u24_e32 v0, 0xe00, v0
	v_lshlrev_b32_e32 v0, 1, v0
	v_lshl_add_u64 v[2:3], s[20:21], 0, v[0:1]
	s_lshl_b32 s6, s17, 7
	v_lshl_add_u64 v[2:3], v[2:3], 0, s[6:7]
	v_lshl_add_u64 v[14:15], v[2:3], 0, v[136:137]
	global_load_dwordx4 v[2:5], v[14:15], off offset:1024
	global_load_dwordx4 v[6:9], v[14:15], off offset:1040
	global_load_dwordx4 v[10:13], v[14:15], off offset:2048
	s_nop 0
	global_load_dwordx4 v[14:17], v[14:15], off offset:2064
	v_ldexp_f32 v0, v18, s15
	v_log_f32_e32 v0, v0
	v_cndmask_b32_e32 v19, 0, v164, vcc
	v_readfirstlane_b32 s6, v223
	s_lshr_b32 s17, s6, 8
	v_sub_f32_e32 v0, v0, v19
	v_mul_f32_e32 v19, v0, v153
	v_cmp_gt_f32_e32 vcc, s27, v19
	s_bfe_u32 s19, s6, 0x10007
	s_mul_i32 s15, s17, 0x4800
	v_cndmask_b32_e32 v19, 0, v163, vcc
	v_fmac_f32_e32 v19, v0, v153
	v_exp_f32_e32 v0, v19
	v_lshl_or_b32 v18, s19, 6, v158
	s_add_i32 s15, s15, 0
	v_add3_u32 v30, s15, v18, v154
	v_cndmask_b32_e32 v18, 0, v165, vcc
	v_ldexp_f32 v0, v0, v18
	s_lshr_b32 s6, s6, 1
	s_and_b32 s6, s6, 32
	v_or_b32_e32 v27, s6, v151
	v_lshl_or_b32 v26, s19, 11, v148
	s_lshl_b32 s18, s18, 6
	s_or_b32 s14, s18, s14
	s_waitcnt vmcnt(1)
	ds_write_b128 v160, v[10:13] offset:9216
	s_waitcnt vmcnt(0)
	ds_write_b128 v160, v[14:17] offset:9232
	v_lshlrev_b32_e32 v18, 16, v2
	v_and_b32_e32 v19, 0xffff0000, v2
	v_lshlrev_b32_e32 v2, 16, v3
	v_and_b32_e32 v3, 0xffff0000, v3
	v_lshlrev_b32_e32 v20, 16, v4
	v_and_b32_e32 v21, 0xffff0000, v4
	v_lshlrev_b32_e32 v4, 16, v5
	v_and_b32_e32 v5, 0xffff0000, v5
	v_lshlrev_b32_e32 v22, 16, v6
	v_and_b32_e32 v23, 0xffff0000, v6
	v_lshlrev_b32_e32 v6, 16, v7
	v_and_b32_e32 v7, 0xffff0000, v7
	v_lshlrev_b32_e32 v24, 16, v8
	v_and_b32_e32 v25, 0xffff0000, v8
	v_lshlrev_b32_e32 v8, 16, v9
	v_and_b32_e32 v9, 0xffff0000, v9
	v_pk_mul_f32 v[10:11], v[0:1], v[18:19] op_sel_hi:[0,1]
	v_pk_mul_f32 v[12:13], v[0:1], v[2:3] op_sel_hi:[0,1]
	v_pk_mul_f32 v[14:15], v[0:1], v[20:21] op_sel_hi:[0,1]
	v_pk_mul_f32 v[16:17], v[0:1], v[4:5] op_sel_hi:[0,1]
	v_pk_mul_f32 v[18:19], v[0:1], v[22:23] op_sel_hi:[0,1]
	v_pk_mul_f32 v[20:21], v[0:1], v[6:7] op_sel_hi:[0,1]
	v_pk_mul_f32 v[22:23], v[0:1], v[24:25] op_sel_hi:[0,1]
	v_pk_mul_f32 v[24:25], v[0:1], v[8:9] op_sel_hi:[0,1]
	v_cvt_pk_bf16_f32 v2, v10, v11
	v_cvt_pk_bf16_f32 v3, v12, v13
	v_cvt_pk_bf16_f32 v4, v14, v15
	v_cvt_pk_bf16_f32 v5, v16, v17
	v_cvt_pk_bf16_f32 v6, v18, v19
	v_cvt_pk_bf16_f32 v7, v20, v21
	v_cvt_pk_bf16_f32 v8, v22, v23
	v_cvt_pk_bf16_f32 v9, v24, v25
	ds_write_b128 v160, v[2:5]
	ds_write_b128 v160, v[6:9] offset:16
	s_waitcnt lgkmcnt(0)
	s_barrier
	ds_read_b64_tr_b16 v[2:3], v30 offset:9216
	ds_read_b64_tr_b16 v[4:5], v30 offset:9792
	v_lshlrev_b32_e32 v0, 1, v27
	v_add3_u32 v32, s15, v0, v154
	ds_read_b64_tr_b16 v[6:7], v32
	ds_read_b64_tr_b16 v[8:9], v32 offset:576
	ds_read_b64_tr_b16 v[18:19], v30 offset:11520
	ds_read_b64_tr_b16 v[20:21], v30 offset:12096
	ds_read_b64_tr_b16 v[22:23], v32 offset:2304
	ds_read_b64_tr_b16 v[24:25], v32 offset:2880
	s_waitcnt lgkmcnt(4)
	v_mfma_f32_32x32x16_bf16 v[2:17], v[2:5], v[6:9], 0
	v_or_b32_e32 v0, s6, v26
	ds_read_b64_tr_b16 v[26:27], v30 offset:13824
	ds_read_b64_tr_b16 v[28:29], v30 offset:14400
	s_add_i32 s6, s14, s17
	s_lshl_b64 s[14:15], s[6:7], 14
	s_add_u32 s14, s50, s14
	v_lshlrev_b32_e32 v0, 2, v0
	s_addc_u32 s15, s51, s15
	s_waitcnt lgkmcnt(2)
	v_mfma_f32_32x32x16_bf16 v[2:17], v[18:21], v[22:25], v[2:17]
	ds_read_b64_tr_b16 v[18:19], v32 offset:4608
	ds_read_b64_tr_b16 v[20:21], v32 offset:5184
	ds_read_b64_tr_b16 v[22:23], v30 offset:16128
	ds_read_b64_tr_b16 v[24:25], v30 offset:16704
	ds_read_b64_tr_b16 v[30:31], v32 offset:6912
	ds_read_b64_tr_b16 v[32:33], v32 offset:7488
	s_waitcnt lgkmcnt(4)
	v_mfma_f32_32x32x16_bf16 v[2:17], v[26:29], v[18:21], v[2:17]
	v_lshl_add_u64 v[18:19], s[14:15], 0, v[0:1]
	v_add_co_u32_e32 v18, vcc, s48, v18
	s_nop 1
	v_addc_co_u32_e32 v19, vcc, 0, v19, vcc
	s_waitcnt lgkmcnt(0)
	v_mfma_f32_32x32x16_bf16 v[2:17], v[22:25], v[30:33], v[2:17]
	s_nop 11
	global_store_dword v0, v2, s[14:15]
	global_store_dword v0, v3, s[14:15] offset:256
	global_store_dword v0, v4, s[14:15] offset:512
	global_store_dword v0, v5, s[14:15] offset:768
	global_store_dword v0, v6, s[14:15] offset:2048
	global_store_dword v0, v7, s[14:15] offset:2304
	global_store_dword v0, v8, s[14:15] offset:2560
	global_store_dword v0, v9, s[14:15] offset:2816
	global_store_dword v[18:19], v10, off
	global_store_dword v[18:19], v11, off offset:256
	global_store_dword v[18:19], v12, off offset:512
	global_store_dword v[18:19], v13, off offset:768
	global_store_dword v[18:19], v14, off offset:2048
	global_store_dword v[18:19], v15, off offset:2304
	global_store_dword v[18:19], v16, off offset:2560
	global_store_dword v[18:19], v17, off offset:2816
	s_barrier
	s_mov_b64 s[14:15], 0

.LBB0_463:
	s_and_b64 vcc, exec, s[16:17]
	s_cbranch_vccnz .Lq_more
	s_and_saveexec_b64 s[98:99], s[90:91]
	s_cbranch_execz .Lq_fx
	v_mov_b32_e32 v200, 1
	global_atomic_add v199, v1, v200, s[8:9] sc0
.Lq_fx:
	s_or_b64 exec, exec, s[98:99]

	.amdhsa_kernel _Z9hymba_fwd6Paramsiii
		.amdhsa_group_segment_fixed_size 0
		.amdhsa_private_segment_fixed_size 0
		.amdhsa_kernarg_size 448
		.amdhsa_user_sgpr_count 2
		.amdhsa_user_sgpr_dispatch_ptr 0
		.amdhsa_user_sgpr_queue_ptr 0
		.amdhsa_user_sgpr_kernarg_segment_ptr 1
		.amdhsa_user_sgpr_dispatch_id 0
		.amdhsa_user_sgpr_kernarg_preload_length 0
		.amdhsa_user_sgpr_kernarg_preload_offset 0
		.amdhsa_user_sgpr_private_segment_size 0
		.amdhsa_uses_dynamic_stack 0
		.amdhsa_enable_private_segment 0
		.amdhsa_system_sgpr_workgroup_id_x 1
		.amdhsa_system_sgpr_workgroup_id_y 0
		.amdhsa_system_sgpr_workgroup_id_z 0
		.amdhsa_system_sgpr_workgroup_info 0
		.amdhsa_system_vgpr_workitem_id 2
		.amdhsa_next_free_vgpr 253
		.amdhsa_next_free_sgpr 102
		.amdhsa_accum_offset 256
		.amdhsa_reserve_vcc 1
		.amdhsa_float_round_mode_32 0
		.amdhsa_float_round_mode_16_64 0
		.amdhsa_float_denorm_mode_32 3
		.amdhsa_float_denorm_mode_16_64 3
		.amdhsa_dx10_clamp 1
		.amdhsa_ieee_mode 1
		.amdhsa_fp16_overflow 0
		.amdhsa_tg_split 0
		.amdhsa_exception_fp_ieee_invalid_op 0
		.amdhsa_exception_fp_denorm_src 0
		.amdhsa_exception_fp_ieee_div_zero 0
		.amdhsa_exception_fp_ieee_overflow 0
		.amdhsa_exception_fp_ieee_underflow 0
		.amdhsa_exception_fp_ieee_inexact 0
		.amdhsa_exception_int_div_zero 0
	.end_amdhsa_kernel

amdhsa.kernels:
  - .agpr_count:     0
    .args:
      - .offset:         0
        .size:           176
        .value_kind:     by_value
      - .offset:         176
        .size:           4
        .value_kind:     by_value
      - .offset:         180
        .size:           4
        .value_kind:     by_value
      - .offset:         184
        .size:           4
        .value_kind:     by_value
      - .offset:         192
        .size:           4
        .value_kind:     hidden_block_count_x
      - .offset:         196
        .size:           4
        .value_kind:     hidden_block_count_y
      - .offset:         200
        .size:           4
        .value_kind:     hidden_block_count_z
      - .offset:         204
        .size:           2
        .value_kind:     hidden_group_size_x
      - .offset:         206
        .size:           2
        .value_kind:     hidden_group_size_y
      - .offset:         208
        .size:           2
        .value_kind:     hidden_group_size_z
      - .offset:         210
        .size:           2
        .value_kind:     hidden_remainder_x
      - .offset:         212
        .size:           2
        .value_kind:     hidden_remainder_y
      - .offset:         214
        .size:           2
        .value_kind:     hidden_remainder_z
      - .offset:         232
        .size:           8
        .value_kind:     hidden_global_offset_x
      - .offset:         240
        .size:           8
        .value_kind:     hidden_global_offset_y
      - .offset:         248
        .size:           8
        .value_kind:     hidden_global_offset_z
      - .offset:         256
        .size:           2
        .value_kind:     hidden_grid_dims
      - .offset:         280
        .size:           8
        .value_kind:     hidden_multigrid_sync_arg
      - .offset:         312
        .size:           4
        .value_kind:     hidden_dynamic_lds_size
    .group_segment_fixed_size: 0
    .kernarg_segment_align: 8
    .kernarg_segment_size: 448
    .language:       OpenCL C
    .language_version:
      - 2
      - 0
    .max_flat_workgroup_size: 512
    .name:           _Z9hymba_fwd6Paramsiii
    .private_segment_fixed_size: 0
    .sgpr_count:     108
    .sgpr_spill_count: 42
    .symbol:         _Z9hymba_fwd6Paramsiii.kd
    .uniform_work_group_size: 1
    .uses_dynamic_stack: false
    .vgpr_count:     253
    .vgpr_spill_count: 0
    .wavefront_size: 64
